# v071 plus finalize items split: scan blocks take one finalize item after their scan
# baseline (speedup 1.0000x reference)
; __global__ void __launch_bounds__(NTHR, 2) fwd_megakernel(Params p) {
;     ...
;         if ((!big || p.bid >= 128) && rep == 0) {
;           const int cL0 = L, cj0 = (L & 1) ? 2 : 1, cL1 = (L < 3) ? L + 1 : 3, cj1 = (L == 3) ? 4 : ((L & 1) ? 0 : 1);
;           cvt_jobs(p, cL0, cj0, cL1, cj1, vb, VG);
;         }
;         if ((!big || p.bid >= 128) && rep == nrep - 1) {
;           for (int it = vb; it < 256; it += VG) {
;             if (kind == 3) ab_fin_rows(p, L, it * 128, 128, false, true); else cd_fin_rows(p, L, it * 128, 128, false, true);
;           }
;         }
.LBB0_350:
	v_readlane_b32 s0, v253, 45
	s_addk_i32 s66, 0x100
	s_add_i32 s18, s18, s0
	s_cmpk_gt_i32 s66, 0xff
	s_cbranch_scc1 .LBB0_364

; __global__ void __launch_bounds__(NTHR, 2) fwd_megakernel(Params p) {
;     ...
;         if (!big || p.bid < 128) {
;           for (int it = p.bid; it < 128; it += (big ? 128 : G)) {
;             const int item = (it & 7) * 16 + (it >> 3);
;             if (kind == 3) dn_scan_block(p, L, item); else hg_scan_block(p, L, item);
;           }
;         }
;         if ((!big || p.bid >= 128) && rep == 0) {
;           const int cL0 = L, cj0 = (L & 1) ? 2 : 1, cL1 = (L < 3) ? L + 1 : 3, cj1 = (L == 3) ? 4 : ((L & 1) ? 0 : 1);
;           cvt_jobs(p, cL0, cj0, cL1, cj1, vb, VG);
;         }
;         if ((!big || p.bid >= 128) && rep == nrep - 1) {
;           for (int it = vb; it < 256; it += VG) {
;             if (kind == 3) ab_fin_rows(p, L, it * 128, 128, false, true); else cd_fin_rows(p, L, it * 128, 128, false, true);
;           }
.Lscan_fin_entry:
	v_writelane_b32 v255, s70, 6
	v_readlane_b32 s66, v254, 55
	s_nop 1
	s_addk_i32 s66, 0x80
	s_branch .LBB0_347
